# phase F: hand-written epilogue, residual loads 16 in flight with counted vmcnt instead of 32 serial load-wait-store round trips
# speedup vs baseline: 1.0064x; 1.0061x over previous
; __device__ __forceinline__ void phaseF(const Params& p, int layer) {
;     ...
; #pragma unroll
;     for (int ai = 0; ai < 2; ai++)
; #pragma unroll
;       for (int m = 0; m < 4; m++) {
;         const size_t tok = brow + ai * 128 + wr * 64 + m * 16 + fr;
; #pragma unroll
;         for (int bj = 0; bj < 2; bj++)
; #pragma unroll
;           for (int n = 0; n < 2; n++) {
;             const int col = bcol + bj * 128 + wc * 32 + n * 16 + fq * 4;
;             float4 xr = *(const float4*)(xres + tok * 2048 + col);
;             f32x4 v = acc[ai][bj][m][n];
;             float4 o;
;             o.x = 1.41421356237f * xr.x + v[0]; o.y = 1.41421356237f * xr.y + v[1];
;             o.z = 1.41421356237f * xr.z + v[2]; o.w = 1.41421356237f * xr.w + v[3];
;             *(float4*)(p.out + tok * 2048 + col) = o;
;           }
;       }
.LBB0_2433:
	v_add_u32_e32 v130, s2, v138
	v_or_b32_e32 v128, s4, v139
	v_ashrrev_i32_e32 v131, 31, v130
	v_lshlrev_b64 v[136:137], 13, v[130:131]
	v_ashrrev_i32_e32 v129, 31, v128
	v_lshl_add_u64 v[132:133], s[0:1], 0, v[136:137]
	v_lshlrev_b64 v[128:129], 2, v[128:129]
	v_lshl_add_u64 v[140:141], v[132:133], 0, v[128:129]
	v_readlane_b32 s52, v252, 48
	v_readlane_b32 s60, v252, 56
	v_readlane_b32 s61, v252, 57
	v_readlane_b32 s62, v252, 58
	v_readlane_b32 s63, v252, 59
	v_readlane_b32 s64, v252, 60
	v_readlane_b32 s65, v252, 61
	v_readlane_b32 s66, v252, 62
	v_readlane_b32 s67, v252, 63
	s_mov_b64 s[20:21], s[60:61]
	s_mov_b64 s[22:23], s[62:63]
	v_lshl_add_u64 v[136:137], s[22:23], 0, v[136:137]
	v_lshl_add_u64 v[136:137], v[136:137], 0, v[128:129]
	v_readlane_b32 s2, v253, 2
	s_add_i32 s16, s16, s2
	s_cmpk_lt_i32 s16, 0x400
	v_readlane_b32 s53, v252, 49
	v_readlane_b32 s54, v252, 50
	v_readlane_b32 s55, v252, 51
	v_readlane_b32 s56, v252, 52
	v_readlane_b32 s57, v252, 53
	v_readlane_b32 s58, v252, 54
	v_readlane_b32 s59, v252, 55
	s_mov_b64 s[24:25], s[64:65]
	s_mov_b64 s[26:27], s[66:67]
	v_mov_b32_e32 v200, v140
	v_mov_b32_e32 v201, v141
	global_load_dwordx4 v[128:131], v[200:201], off
	global_load_dwordx4 v[132:135], v[200:201], off offset:64
	global_load_dwordx4 v[148:151], v[200:201], off offset:512
	global_load_dwordx4 v[152:155], v[200:201], off offset:576
	v_add_co_u32_e32 v220, vcc, 0x20000, v140
	s_nop 1
	v_addc_co_u32_e32 v221, vcc, 0, v141, vcc
	global_load_dwordx4 v[156:159], v[220:221], off
	global_load_dwordx4 v[164:167], v[220:221], off offset:64
	global_load_dwordx4 v[168:171], v[220:221], off offset:512
	global_load_dwordx4 v[172:175], v[220:221], off offset:576
	v_add_co_u32_e32 v224, vcc, 0x40000, v140
	s_nop 1
	v_addc_co_u32_e32 v225, vcc, 0, v141, vcc
	global_load_dwordx4 v[176:179], v[224:225], off
	global_load_dwordx4 v[180:183], v[224:225], off offset:64
	global_load_dwordx4 v[184:187], v[224:225], off offset:512
	global_load_dwordx4 v[188:191], v[224:225], off offset:576
	v_add_co_u32_e32 v228, vcc, 0x60000, v140
	s_nop 1
	v_addc_co_u32_e32 v229, vcc, 0, v141, vcc
	global_load_dwordx4 v[192:195], v[228:229], off
	global_load_dwordx4 v[196:199], v[228:229], off offset:64
	global_load_dwordx4 v[212:215], v[228:229], off offset:512
	global_load_dwordx4 v[216:219], v[228:229], off offset:576
	v_mov_b32_e32 v204, v136
	v_mov_b32_e32 v205, v137
	s_waitcnt vmcnt(12)
	v_pk_fma_f32 v[120:121], v[128:129], s[28:29], v[120:121] op_sel_hi:[1,0,1]
	v_pk_fma_f32 v[122:123], v[130:131], s[28:29], v[122:123] op_sel_hi:[1,0,1]
	v_pk_fma_f32 v[116:117], v[132:133], s[28:29], v[116:117] op_sel_hi:[1,0,1]
	v_pk_fma_f32 v[118:119], v[134:135], s[28:29], v[118:119] op_sel_hi:[1,0,1]
	v_pk_fma_f32 v[124:125], v[148:149], s[28:29], v[124:125] op_sel_hi:[1,0,1]
	v_pk_fma_f32 v[126:127], v[150:151], s[28:29], v[126:127] op_sel_hi:[1,0,1]
	v_pk_fma_f32 v[112:113], v[152:153], s[28:29], v[112:113] op_sel_hi:[1,0,1]
	v_pk_fma_f32 v[114:115], v[154:155], s[28:29], v[114:115] op_sel_hi:[1,0,1]
	global_store_dwordx4 v[204:205], v[120:123], off
	global_store_dwordx4 v[204:205], v[116:119], off offset:64
	global_store_dwordx4 v[204:205], v[124:127], off offset:512
	global_store_dwordx4 v[204:205], v[112:115], off offset:576
	v_add_co_u32_e32 v200, vcc, 0x100000, v140
	s_nop 1
	v_addc_co_u32_e32 v201, vcc, 0, v141, vcc
	global_load_dwordx4 v[128:131], v[200:201], off
	global_load_dwordx4 v[132:135], v[200:201], off offset:64
	global_load_dwordx4 v[148:151], v[200:201], off offset:512
	global_load_dwordx4 v[152:155], v[200:201], off offset:576
	v_add_co_u32_e32 v232, vcc, 0x20000, v136
	s_nop 1
	v_addc_co_u32_e32 v233, vcc, 0, v137, vcc
	s_waitcnt vmcnt(16)
	v_pk_fma_f32 v[104:105], v[156:157], s[28:29], v[104:105] op_sel_hi:[1,0,1]
	v_pk_fma_f32 v[106:107], v[158:159], s[28:29], v[106:107] op_sel_hi:[1,0,1]
	v_pk_fma_f32 v[100:101], v[164:165], s[28:29], v[100:101] op_sel_hi:[1,0,1]
	v_pk_fma_f32 v[102:103], v[166:167], s[28:29], v[102:103] op_sel_hi:[1,0,1]
	v_pk_fma_f32 v[108:109], v[168:169], s[28:29], v[108:109] op_sel_hi:[1,0,1]
	v_pk_fma_f32 v[110:111], v[170:171], s[28:29], v[110:111] op_sel_hi:[1,0,1]
	v_pk_fma_f32 v[96:97], v[172:173], s[28:29], v[96:97] op_sel_hi:[1,0,1]
	v_pk_fma_f32 v[98:99], v[174:175], s[28:29], v[98:99] op_sel_hi:[1,0,1]
	global_store_dwordx4 v[232:233], v[104:107], off
	global_store_dwordx4 v[232:233], v[100:103], off offset:64
	global_store_dwordx4 v[232:233], v[108:111], off offset:512
	global_store_dwordx4 v[232:233], v[96:99], off offset:576
	v_add_co_u32_e32 v220, vcc, 0x120000, v140
	s_nop 1
	v_addc_co_u32_e32 v221, vcc, 0, v141, vcc
	global_load_dwordx4 v[156:159], v[220:221], off
	global_load_dwordx4 v[164:167], v[220:221], off offset:64
	global_load_dwordx4 v[168:171], v[220:221], off offset:512
	global_load_dwordx4 v[172:175], v[220:221], off offset:576
	v_add_co_u32_e32 v204, vcc, 0x40000, v136
	s_nop 1
	v_addc_co_u32_e32 v205, vcc, 0, v137, vcc
	s_waitcnt vmcnt(20)
; __device__ __forceinline__ void phaseF(const Params& p, int layer) {
;     ...
; #pragma unroll
;     for (int ai = 0; ai < 2; ai++)
; #pragma unroll
;       for (int m = 0; m < 4; m++) {
;         const size_t tok = brow + ai * 128 + wr * 64 + m * 16 + fr;
; #pragma unroll
;         for (int bj = 0; bj < 2; bj++)
; #pragma unroll
;           for (int n = 0; n < 2; n++) {
;             const int col = bcol + bj * 128 + wc * 32 + n * 16 + fq * 4;
;             float4 xr = *(const float4*)(xres + tok * 2048 + col);
;             f32x4 v = acc[ai][bj][m][n];
;             float4 o;
;             o.x = 1.41421356237f * xr.x + v[0]; o.y = 1.41421356237f * xr.y + v[1];
;             o.z = 1.41421356237f * xr.z + v[2]; o.w = 1.41421356237f * xr.w + v[3];
;             *(float4*)(p.out + tok * 2048 + col) = o;
;           }
;       }
	v_pk_fma_f32 v[88:89], v[176:177], s[28:29], v[88:89] op_sel_hi:[1,0,1]
	v_pk_fma_f32 v[90:91], v[178:179], s[28:29], v[90:91] op_sel_hi:[1,0,1]
	v_pk_fma_f32 v[84:85], v[180:181], s[28:29], v[84:85] op_sel_hi:[1,0,1]
	v_pk_fma_f32 v[86:87], v[182:183], s[28:29], v[86:87] op_sel_hi:[1,0,1]
	v_pk_fma_f32 v[92:93], v[184:185], s[28:29], v[92:93] op_sel_hi:[1,0,1]
	v_pk_fma_f32 v[94:95], v[186:187], s[28:29], v[94:95] op_sel_hi:[1,0,1]
	v_pk_fma_f32 v[80:81], v[188:189], s[28:29], v[80:81] op_sel_hi:[1,0,1]
	v_pk_fma_f32 v[82:83], v[190:191], s[28:29], v[82:83] op_sel_hi:[1,0,1]
	global_store_dwordx4 v[204:205], v[88:91], off
	global_store_dwordx4 v[204:205], v[84:87], off offset:64
	global_store_dwordx4 v[204:205], v[92:95], off offset:512
	global_store_dwordx4 v[204:205], v[80:83], off offset:576
	v_add_co_u32_e32 v224, vcc, 0x140000, v140
	s_nop 1
	v_addc_co_u32_e32 v225, vcc, 0, v141, vcc
	global_load_dwordx4 v[176:179], v[224:225], off
	global_load_dwordx4 v[180:183], v[224:225], off offset:64
	global_load_dwordx4 v[184:187], v[224:225], off offset:512
	global_load_dwordx4 v[188:191], v[224:225], off offset:576
	v_add_co_u32_e32 v232, vcc, 0x60000, v136
	s_nop 1
	v_addc_co_u32_e32 v233, vcc, 0, v137, vcc
	s_waitcnt vmcnt(24)
	v_pk_fma_f32 v[72:73], v[192:193], s[28:29], v[72:73] op_sel_hi:[1,0,1]
	v_pk_fma_f32 v[74:75], v[194:195], s[28:29], v[74:75] op_sel_hi:[1,0,1]
	v_pk_fma_f32 v[68:69], v[196:197], s[28:29], v[68:69] op_sel_hi:[1,0,1]
	v_pk_fma_f32 v[70:71], v[198:199], s[28:29], v[70:71] op_sel_hi:[1,0,1]
	v_pk_fma_f32 v[76:77], v[212:213], s[28:29], v[76:77] op_sel_hi:[1,0,1]
	v_pk_fma_f32 v[78:79], v[214:215], s[28:29], v[78:79] op_sel_hi:[1,0,1]
	v_pk_fma_f32 v[60:61], v[216:217], s[28:29], v[60:61] op_sel_hi:[1,0,1]
	v_pk_fma_f32 v[62:63], v[218:219], s[28:29], v[62:63] op_sel_hi:[1,0,1]
	global_store_dwordx4 v[232:233], v[72:75], off
	global_store_dwordx4 v[232:233], v[68:71], off offset:64
	global_store_dwordx4 v[232:233], v[76:79], off offset:512
	global_store_dwordx4 v[232:233], v[60:63], off offset:576
	v_add_co_u32_e32 v228, vcc, 0x160000, v140
	s_nop 1
	v_addc_co_u32_e32 v229, vcc, 0, v141, vcc
	global_load_dwordx4 v[192:195], v[228:229], off
	global_load_dwordx4 v[196:199], v[228:229], off offset:64
	global_load_dwordx4 v[212:215], v[228:229], off offset:512
	global_load_dwordx4 v[216:219], v[228:229], off offset:576
	v_add_co_u32_e32 v204, vcc, 0x100000, v136
	s_nop 1
	v_addc_co_u32_e32 v205, vcc, 0, v137, vcc
	s_waitcnt vmcnt(24)
	v_pk_fma_f32 v[64:65], v[128:129], s[28:29], v[64:65] op_sel_hi:[1,0,1]
	v_pk_fma_f32 v[66:67], v[130:131], s[28:29], v[66:67] op_sel_hi:[1,0,1]
	v_pk_fma_f32 v[52:53], v[132:133], s[28:29], v[52:53] op_sel_hi:[1,0,1]
	v_pk_fma_f32 v[54:55], v[134:135], s[28:29], v[54:55] op_sel_hi:[1,0,1]
	v_pk_fma_f32 v[56:57], v[148:149], s[28:29], v[56:57] op_sel_hi:[1,0,1]
	v_pk_fma_f32 v[58:59], v[150:151], s[28:29], v[58:59] op_sel_hi:[1,0,1]
	v_pk_fma_f32 v[48:49], v[152:153], s[28:29], v[48:49] op_sel_hi:[1,0,1]
	v_pk_fma_f32 v[50:51], v[154:155], s[28:29], v[50:51] op_sel_hi:[1,0,1]
	global_store_dwordx4 v[204:205], v[64:67], off
	global_store_dwordx4 v[204:205], v[52:55], off offset:64
	global_store_dwordx4 v[204:205], v[56:59], off offset:512
	global_store_dwordx4 v[204:205], v[48:51], off offset:576
	v_add_co_u32_e32 v232, vcc, 0x120000, v136
	s_nop 1
	v_addc_co_u32_e32 v233, vcc, 0, v137, vcc
	s_waitcnt vmcnt(20)
	v_pk_fma_f32 v[44:45], v[156:157], s[28:29], v[44:45] op_sel_hi:[1,0,1]
	v_pk_fma_f32 v[46:47], v[158:159], s[28:29], v[46:47] op_sel_hi:[1,0,1]
	v_pk_fma_f32 v[36:37], v[164:165], s[28:29], v[36:37] op_sel_hi:[1,0,1]
	v_pk_fma_f32 v[38:39], v[166:167], s[28:29], v[38:39] op_sel_hi:[1,0,1]
	v_pk_fma_f32 v[40:41], v[168:169], s[28:29], v[40:41] op_sel_hi:[1,0,1]
	v_pk_fma_f32 v[42:43], v[170:171], s[28:29], v[42:43] op_sel_hi:[1,0,1]
	v_pk_fma_f32 v[32:33], v[172:173], s[28:29], v[32:33] op_sel_hi:[1,0,1]
	v_pk_fma_f32 v[34:35], v[174:175], s[28:29], v[34:35] op_sel_hi:[1,0,1]
	global_store_dwordx4 v[232:233], v[44:47], off
	global_store_dwordx4 v[232:233], v[36:39], off offset:64
	global_store_dwordx4 v[232:233], v[40:43], off offset:512
	global_store_dwordx4 v[232:233], v[32:35], off offset:576
	v_add_co_u32_e32 v204, vcc, 0x140000, v136
	s_nop 1
	v_addc_co_u32_e32 v205, vcc, 0, v137, vcc
	s_waitcnt vmcnt(16)
	v_pk_fma_f32 v[28:29], v[176:177], s[28:29], v[28:29] op_sel_hi:[1,0,1]
	v_pk_fma_f32 v[30:31], v[178:179], s[28:29], v[30:31] op_sel_hi:[1,0,1]
	v_pk_fma_f32 v[20:21], v[180:181], s[28:29], v[20:21] op_sel_hi:[1,0,1]
	v_pk_fma_f32 v[22:23], v[182:183], s[28:29], v[22:23] op_sel_hi:[1,0,1]
	v_pk_fma_f32 v[24:25], v[184:185], s[28:29], v[24:25] op_sel_hi:[1,0,1]
	v_pk_fma_f32 v[26:27], v[186:187], s[28:29], v[26:27] op_sel_hi:[1,0,1]
	v_pk_fma_f32 v[16:17], v[188:189], s[28:29], v[16:17] op_sel_hi:[1,0,1]
	v_pk_fma_f32 v[18:19], v[190:191], s[28:29], v[18:19] op_sel_hi:[1,0,1]
	global_store_dwordx4 v[204:205], v[28:31], off
	global_store_dwordx4 v[204:205], v[20:23], off offset:64
	global_store_dwordx4 v[204:205], v[24:27], off offset:512
	global_store_dwordx4 v[204:205], v[16:19], off offset:576
	v_add_co_u32_e32 v232, vcc, 0x160000, v136
	s_nop 1
	v_addc_co_u32_e32 v233, vcc, 0, v137, vcc
	s_waitcnt vmcnt(12)
	v_pk_fma_f32 v[12:13], v[192:193], s[28:29], v[12:13] op_sel_hi:[1,0,1]
	v_pk_fma_f32 v[14:15], v[194:195], s[28:29], v[14:15] op_sel_hi:[1,0,1]
	v_pk_fma_f32 v[4:5], v[196:197], s[28:29], v[4:5] op_sel_hi:[1,0,1]
	v_pk_fma_f32 v[6:7], v[198:199], s[28:29], v[6:7] op_sel_hi:[1,0,1]
	v_pk_fma_f32 v[8:9], v[212:213], s[28:29], v[8:9] op_sel_hi:[1,0,1]
	v_pk_fma_f32 v[10:11], v[214:215], s[28:29], v[10:11] op_sel_hi:[1,0,1]
	v_pk_fma_f32 v[0:1], v[216:217], s[28:29], v[0:1] op_sel_hi:[1,0,1]
	v_pk_fma_f32 v[2:3], v[218:219], s[28:29], v[2:3] op_sel_hi:[1,0,1]
	global_store_dwordx4 v[232:233], v[12:15], off
	global_store_dwordx4 v[232:233], v[4:7], off offset:64
	global_store_dwordx4 v[232:233], v[8:11], off offset:512
	global_store_dwordx4 v[232:233], v[0:3], off offset:576
	s_cbranch_scc0 .LBB0_2440
